# leftover-tile routine: entry drain+barrier moved behind the K loop so its first loads issue immediately
# speedup vs baseline: 1.0173x; 1.0173x over previous
; template <int EPI, int N, int K>
; __device__ __forceinline__ void gemm_phase(const KP& p, int l, const bfr* A, const bfr* Bt) {
;     ...
;   int brow = 0, bcol = 0, pn = 0;
;   if (p.bid < nwg) {
;     TILE_COORDS(p.bid, brow, bcol, pn);
; __device__ void run_phase(const KP& p_, int ph) {
;     ...
;     else if (q == 1) { gemm_phase<2, DM, DFF>(p, l, U, Wl + W_DA); if (l == 0) { plo = 2112; phi = 5440; } else { plo = 7552; phi = 10880; } }
;     else if (q == 3) gemm_phase<3, NINP, DM>(p, l, hb, Wl + W_IN);
;     else if (q == 7) { gemm_phase<2, DM, DM>(p, l, mix, Wl + W_OUT); if (l == 0) { plo = 5440; phi = 6140; } }
;     else if (q == 9) gemm_phase<1, NGU, DM>(p, l, hb, Wl + W_GUB);
;     else { gemm_phase<2, DM, DFF>(p, l, U, Wl + W_DB); if (l == 0) { plo = 6140; phi = 7552; } }
.LBB0_34:
	s_mov_b32 s98, 0x904904
	s_lshr_b32 s98, s98, s68
	s_and_b32 s98, s98, 1
	s_cbranch_scc0 .Lsub_skip
	s_mov_b64 exec, -1
	v_writelane_b32 v174, s4, 0
	v_writelane_b32 v174, s5, 1
	v_writelane_b32 v174, s6, 2
	v_writelane_b32 v174, s7, 3
	v_writelane_b32 v174, s8, 4
	v_writelane_b32 v174, s9, 5
	v_writelane_b32 v174, s10, 6
	v_writelane_b32 v174, s11, 7
	v_writelane_b32 v174, s12, 8
	v_writelane_b32 v174, s13, 9
	v_writelane_b32 v174, s14, 10
	v_writelane_b32 v174, s15, 11
	v_writelane_b32 v174, s16, 12
	v_writelane_b32 v174, s17, 13
	v_writelane_b32 v174, s18, 14
	v_writelane_b32 v174, s19, 15
	v_writelane_b32 v174, s20, 16
	v_writelane_b32 v174, s21, 17
	v_writelane_b32 v174, s22, 18
	v_writelane_b32 v174, s23, 19
	v_writelane_b32 v174, s24, 20
	v_writelane_b32 v174, s25, 21
	v_writelane_b32 v174, s26, 22
	v_writelane_b32 v174, s27, 23
	v_readlane_b32 s20, v255, 45
	v_readlane_b32 s21, v255, 46
	v_readlane_b32 s12, v255, 42
	s_cmp_ge_u32 s68, 13
	s_cselect_b32 s17, 1, 0
	s_mul_i32 s18, s17, 12
	s_sub_i32 s25, s68, s18
	s_add_i32 s25, s25, -1
	s_movk_i32 s11, 0x1600
	s_mov_b32 s9, 6
	s_mov_b32 s10, 1
	s_mov_b32 s18, 0x4329000
	s_mov_b32 s19, 0xb00000
	s_cmp_eq_u32 s25, 10
	s_cselect_b32 s19, 0x2500000, s19
	s_cmp_eq_u32 s25, 7
	s_cselect_b32 s19, 0x1800000, s19
	s_cselect_b32 s18, 0x12a29000, s18
	s_cselect_b32 s11, 0x800, s11
	s_cselect_b32 s9, 2, s9
	s_cselect_b32 s10, 0, s10
	s_mul_i32 s22, s17, 0x2a80000
	s_add_u32 s22, s22, 0x16c29000
	s_add_u32 s22, s22, s19
	s_add_u32 s6, s20, s22
	s_addc_u32 s7, s21, 0
	s_add_u32 s4, s20, s18
	s_addc_u32 s5, s21, 0
	s_and_b32 s13, s12, 15
	s_lshr_b32 s14, s12, 4
	s_and_b32 s15, s13, 7
	s_mul_i32 s15, s15, 0x42
	s_lshr_b32 s16, s13, 3
	s_add_i32 s15, s15, s16
	s_add_i32 s15, s15, 64
	s_lshr_b32 s16, s15, 5
	s_and_b32 s15, s15, 31
	s_cmp_eq_u32 s16, 16
	s_cbranch_scc1 .Lsub_lastgrp
	s_lshl_b32 s16, s16, 3
	s_and_b32 s23, s15, 7
	s_add_i32 s16, s16, s23
	s_lshr_b32 s15, s15, 3
	s_branch .Lsub_havepm

; __device__ __forceinline__ unsigned pack2(float a, float b) { f32v2_t v = {a, b}; bf16v2_t r = __builtin_convertvector(v, bf16v2_t); return __builtin_bit_cast(unsigned, r); }
; template <int EPI, int N, int K>
; __device__ __forceinline__ void gemm_phase(const KP& p, int l, const bfr* A, const bfr* Bt) {
;     ...
;       bfr* hb = (bfr*)(p.ws + OFF_HB);
; #pragma unroll
;       for (int ai = 0; ai < 2; ++ai)
; #pragma unroll
;         for (int m = 0; m < 4; ++m) {
;           int row = erow + ai * HM + wr * 64 + m * 16 + fr;
; #pragma unroll
;           for (int bj = 0; bj < 2; ++bj) {
;             u32x4* hp = (u32x4*)(hb + (size_t)row * DM + ecol + bj * HALF + wc * 32 + fq * 8);
;             u32x4 h = *hp, o;
; #pragma unroll
;             for (int q2 = 0; q2 < 4; ++q2) {
;               f32v2_t hv2 = {__uint_as_float(h[q2] << 16), __uint_as_float(h[q2] & 0xffff0000u)};
;               f32v2_t av2 = {acc[ai][bj][m][q2 >> 1][(q2 & 1) * 2], acc[ai][bj][m][q2 >> 1][(q2 & 1) * 2 + 1]};
;               f32v2_t s2 = hv2 + av2;
;               o[q2] = pack2(s2.x, s2.y);
;             }
;             *hp = o;
.Lsub_kdone:
	s_nop 7
	s_nop 7
	s_waitcnt lgkmcnt(0)
	s_barrier
	v_and_b32_e32 v248, 63, v156
	v_lshlrev_b32_e32 v248, 4, v248
	s_lshl_b32 s17, s24, 14
	v_add_u32_e32 v249, s17, v248
	ds_write_b128 v249, v[4:7]
	ds_write_b128 v249, v[8:11] offset:1024
	ds_write_b128 v249, v[12:15] offset:2048
	ds_write_b128 v249, v[16:19] offset:3072
	ds_write_b128 v249, v[20:23] offset:4096
	ds_write_b128 v249, v[24:27] offset:5120
	ds_write_b128 v249, v[28:31] offset:6144
	ds_write_b128 v249, v[32:35] offset:7168
	ds_write_b128 v249, v[36:39] offset:8192
	ds_write_b128 v249, v[40:43] offset:9216
	ds_write_b128 v249, v[44:47] offset:10240
	ds_write_b128 v249, v[48:51] offset:11264
	ds_write_b128 v249, v[52:55] offset:12288
	ds_write_b128 v249, v[56:59] offset:13312
	ds_write_b128 v249, v[60:63] offset:14336
	ds_write_b128 v249, v[64:67] offset:15360
	s_waitcnt lgkmcnt(0)
	s_barrier
	s_lshr_b32 s17, s24, 2
	s_lshl_b32 s17, s17, 3
	s_and_b32 s18, s24, 3
	s_add_i32 s17, s17, s18
	s_lshl_b32 s17, s17, 10
	v_add_u32_e32 v250, s17, v248
	v_add_u32_e32 v251, 0x10000, v250
	ds_read_b128 v[68:71], v250
	ds_read_b128 v[72:75], v250 offset:16384
	ds_read_b128 v[76:79], v250 offset:32768
	ds_read_b128 v[80:83], v250 offset:49152
	ds_read_b128 v[84:87], v251
	ds_read_b128 v[88:91], v251 offset:16384
	ds_read_b128 v[92:95], v251 offset:32768
	ds_read_b128 v[96:99], v251 offset:49152
	ds_read_b128 v[100:103], v250 offset:4096
	ds_read_b128 v[104:107], v250 offset:20480
	ds_read_b128 v[108:111], v250 offset:36864
	ds_read_b128 v[112:115], v250 offset:53248
	ds_read_b128 v[116:119], v251 offset:4096
	ds_read_b128 v[120:123], v251 offset:20480
	ds_read_b128 v[124:127], v251 offset:36864
	ds_read_b128 v[128:131], v251 offset:53248
	s_and_b32 s18, s24, 3
	s_lshl_b32 s18, s18, 4
	s_add_i32 s18, s18, s16
	v_and_b32_e32 v252, 15, v156
	v_add_u32_e32 v252, s18, v252
	v_lshlrev_b32_e32 v252, 11, v252
	s_lshr_b32 s17, s24, 2
	s_lshl_b32 s17, s17, 5
	s_add_i32 s17, s17, s15
	v_bfe_u32 v253, v156, 4, 2
	v_lshl_add_u32 v253, v253, 3, s17
	v_lshl_add_u32 v252, v253, 1, v252
	global_load_dwordx4 v[132:135], v252, s[20:21]
	s_waitcnt lgkmcnt(0)
	v_add_f32_e32 v68, v68, v72
	v_add_f32_e32 v100, v100, v104
	v_add_f32_e32 v69, v69, v73
	v_add_f32_e32 v101, v101, v105
	v_add_f32_e32 v70, v70, v74
	v_add_f32_e32 v102, v102, v106
	v_add_f32_e32 v71, v71, v75
	v_add_f32_e32 v103, v103, v107
	v_add_f32_e32 v68, v68, v76
	v_add_f32_e32 v100, v100, v108
	v_add_f32_e32 v69, v69, v77
	v_add_f32_e32 v101, v101, v109
	v_add_f32_e32 v70, v70, v78
	v_add_f32_e32 v102, v102, v110
	v_add_f32_e32 v71, v71, v79
	v_add_f32_e32 v103, v103, v111
	v_add_f32_e32 v68, v68, v80
	v_add_f32_e32 v100, v100, v112
	v_add_f32_e32 v69, v69, v81
	v_add_f32_e32 v101, v101, v113
	v_add_f32_e32 v70, v70, v82
	v_add_f32_e32 v102, v102, v114
	v_add_f32_e32 v71, v71, v83
	v_add_f32_e32 v103, v103, v115
	v_add_f32_e32 v68, v68, v84
	v_add_f32_e32 v100, v100, v116
	v_add_f32_e32 v69, v69, v85
	v_add_f32_e32 v101, v101, v117
	v_add_f32_e32 v70, v70, v86
	v_add_f32_e32 v102, v102, v118
	v_add_f32_e32 v71, v71, v87
	v_add_f32_e32 v103, v103, v119
	v_add_f32_e32 v68, v68, v88
	v_add_f32_e32 v100, v100, v120
	v_add_f32_e32 v69, v69, v89
	v_add_f32_e32 v101, v101, v121
	v_add_f32_e32 v70, v70, v90
	v_add_f32_e32 v102, v102, v122
	v_add_f32_e32 v71, v71, v91
	v_add_f32_e32 v103, v103, v123
	v_add_f32_e32 v68, v68, v92
	v_add_f32_e32 v100, v100, v124
	v_add_f32_e32 v69, v69, v93
	v_add_f32_e32 v101, v101, v125
	v_add_f32_e32 v70, v70, v94
	v_add_f32_e32 v102, v102, v126
	v_add_f32_e32 v71, v71, v95
	v_add_f32_e32 v103, v103, v127
	v_add_f32_e32 v68, v68, v96
	v_add_f32_e32 v100, v100, v128
	v_add_f32_e32 v69, v69, v97
	v_add_f32_e32 v101, v101, v129
	v_add_f32_e32 v70, v70, v98
	v_add_f32_e32 v102, v102, v130
	v_add_f32_e32 v71, v71, v99
	v_add_f32_e32 v103, v103, v131
	s_waitcnt vmcnt(0)
	v_lshlrev_b32_e32 v248, 16, v132
	v_and_b32_e32 v249, 0xffff0000, v132
	v_add_f32_e32 v248, v248, v68
	v_add_f32_e32 v249, v249, v69
	v_cvt_pk_bf16_f32 v136, v248, v249
	v_lshlrev_b32_e32 v248, 16, v133
	v_and_b32_e32 v249, 0xffff0000, v133
	v_add_f32_e32 v248, v248, v70
	v_add_f32_e32 v249, v249, v71
	v_cvt_pk_bf16_f32 v137, v248, v249
	v_lshlrev_b32_e32 v248, 16, v134
	v_and_b32_e32 v249, 0xffff0000, v134
	v_add_f32_e32 v248, v248, v100
	v_add_f32_e32 v249, v249, v101
	v_cvt_pk_bf16_f32 v138, v248, v249
	v_lshlrev_b32_e32 v248, 16, v135
	v_and_b32_e32 v249, 0xffff0000, v135
	v_add_f32_e32 v248, v248, v102
	v_add_f32_e32 v249, v249, v103
	v_cvt_pk_bf16_f32 v139, v248, v249
	global_store_dwordx4 v252, v[136:139], s[20:21]
	s_waitcnt lgkmcnt(0)
	s_barrier
	v_readlane_b32 s4, v174, 0
	v_readlane_b32 s5, v174, 1
	v_readlane_b32 s6, v174, 2
	v_readlane_b32 s7, v174, 3
	v_readlane_b32 s8, v174, 4
	v_readlane_b32 s9, v174, 5
	v_readlane_b32 s10, v174, 6
	v_readlane_b32 s11, v174, 7
	v_readlane_b32 s12, v174, 8
	v_readlane_b32 s13, v174, 9
	v_readlane_b32 s14, v174, 10
	v_readlane_b32 s15, v174, 11
	v_readlane_b32 s16, v174, 12
	v_readlane_b32 s17, v174, 13
	v_readlane_b32 s18, v174, 14
	v_readlane_b32 s19, v174, 15
	v_readlane_b32 s20, v174, 16
	v_readlane_b32 s21, v174, 17
	v_readlane_b32 s22, v174, 18
	v_readlane_b32 s23, v174, 19
	v_readlane_b32 s24, v174, 20
	v_readlane_b32 s25, v174, 21
	v_readlane_b32 s26, v174, 22
	v_readlane_b32 s27, v174, 23
	s_nop 3
